# v8 + one static s_setprio 1 for waves 0-3 (instead of 4-7) for the whole attention phase
# baseline (speedup 1.0000x reference)
; #define LAS __attribute__((address_space(3)))
; __global__ void __launch_bounds__(NTHREADS, 2) fwd_kernel(Args args) {
;     ...
;     if (IN(3)) for (int rep = 0; rep < NREP(3); ++rep) {
;         char* al = (char*)lds;
;         LAS float* FL = (LAS float*)(L + att::OFF_FL);
;         LAS float* TB = (LAS float*)(L + att::OFF_TB);
;         volatile LAS int* QW = (volatile LAS int*)(L + att::OFF_QW);
;         bf16* QAb = QKV; bf16* KAb = QKV + QKV_STRIDE; bf16* VAb = QKV + 2 * QKV_STRIDE; bf16* QBb = QKV + 3 * QKV_STRIDE; bf16* KBb = QKV + 4 * QKV_STRIDE; bf16* VBb = QKV + 5 * QKV_STRIDE;
;         unsigned char* OA8 = (unsigned char*)Hb; unsigned char* OB8 = OA8 + QKV_STRIDE_B;
;         const float* rel = arg_in(14);
;         att::Seam S;
;         if (vcu < 256) {
.LBB0_641:
	v_readlane_b32 s100, v255, 5
	s_nop 3
	s_cmp_lt_u32 s100, 4
	s_cbranch_scc0 .Lp3_prio_done
	s_setprio 1
